# attention step heads: post-barrier VALU (LDS address adds, row-sum carry) moved ahead of the step wait and barrier so each step leads with its K-fragment reads
# baseline (speedup 1.0000x reference)
.LBB0_649:
	s_add_i32 s18, s97, 0xfffe8000
	s_and_b32 s18, s18, 0x18000
	s_add_i32 vcc_hi, s18, 0
	v_add_u32_e32 v132, vcc_hi, v144
	v_add_u32_e32 v136, vcc_hi, v159
	v_add_u32_e32 v133, vcc_hi, v157
	v_add_u32_e32 v137, vcc_hi, v160
	s_waitcnt vmcnt(4) lgkmcnt(0)
	s_barrier
	ds_read_b128 v[96:99], v132
	ds_read_b128 v[100:103], v133
	ds_read_b128 v[104:107], v136
	ds_read_b128 v[108:111], v137
	s_and_b32 s26, s97, 0x18000
	s_add_i32 vcc_lo, s61, 2
	s_add_i32 s18, s26, 0
	ds_read_b128 v[202:205], v132 offset:4096
	ds_read_b128 v[206:209], v133 offset:4096
	s_waitcnt lgkmcnt(5)
	v_mfma_f32_32x32x16_bf16 v[80:95], v[96:99], v[124:127], v[0:15]
	v_cvt_pk_bf16_f32 v128, v194, v195
	v_cvt_pk_bf16_f32 v129, v196, v197
	v_cvt_pk_bf16_f32 v130, v198, v200
	v_cvt_pk_bf16_f32 v131, v199, v201
	ds_read_b128 v[210:213], v136 offset:4096
	ds_read_b128 v[214:217], v137 offset:4096
	s_waitcnt lgkmcnt(6)
	v_mfma_f32_32x32x16_bf16 v[80:95], v[100:103], v[120:123], v[80:95]
	v_cvt_pk_bf16_f32 v132, v180, v181
	v_cvt_pk_bf16_f32 v133, v182, v183
	v_cvt_pk_bf16_f32 v134, v193, v189
	v_cvt_pk_bf16_f32 v135, v190, v192
	v_add_u32_e32 v234, s18, v167
	v_add_u32_e32 v235, s18, v168
	ds_read_b128 v[218:221], v234 offset:16384
	ds_read_b128 v[222:225], v235 offset:16384
	s_waitcnt lgkmcnt(7)
	v_mfma_f32_32x32x16_bf16 v[80:95], v[104:107], v[116:119], v[80:95]
	v_cvt_pk_bf16_f32 v136, v173, v174
	v_cvt_pk_bf16_f32 v137, v175, v176
	v_cvt_pk_bf16_f32 v138, v191, v188
	v_cvt_pk_bf16_f32 v139, v171, v172
	v_add_u32_e32 v236, s18, v169
	v_add_u32_e32 v237, s18, v170
	ds_read_b128 v[226:229], v236 offset:16384
	ds_read_b128 v[230:233], v237 offset:16384
	s_waitcnt lgkmcnt(8)
	v_mfma_f32_32x32x16_bf16 v[80:95], v[108:111], v[112:115], v[80:95]
	v_cvt_pk_bf16_f32 v140, v185, v186
	v_cvt_pk_bf16_f32 v141, v187, v184
	v_cvt_pk_bf16_f32 v142, v177, v178
	v_cvt_pk_bf16_f32 v143, v179, v161
	v_add_f32_e32 v96, 0, v194
	v_add_f32_e32 v96, v195, v96
	v_add_f32_e32 v96, v196, v96
	v_add_f32_e32 v96, v197, v96
	v_add_f32_e32 v96, v198, v96
	v_add_f32_e32 v194, v200, v96
	v_add_f32_e32 v194, v199, v194
	v_add_f32_e32 v194, v201, v194
	s_waitcnt lgkmcnt(7)
	v_mfma_f32_32x32x16_bf16 v[96:111], v[202:205], v[124:127], v[0:15]
	v_exp_f32_e32 v195, v80
	v_exp_f32_e32 v196, v81
	v_exp_f32_e32 v197, v82
	v_exp_f32_e32 v198, v83
	s_waitcnt lgkmcnt(6)
	v_mfma_f32_32x32x16_bf16 v[96:111], v[206:209], v[120:123], v[96:111]
	v_exp_f32_e32 v199, v84
	v_exp_f32_e32 v200, v85
	v_exp_f32_e32 v201, v86
	s_waitcnt lgkmcnt(5)
	v_mfma_f32_32x32x16_bf16 v[96:111], v[210:213], v[116:119], v[96:111]
	v_exp_f32_e32 v238, v87
	s_waitcnt lgkmcnt(4)
	v_mfma_f32_32x32x16_bf16 v[96:111], v[214:217], v[112:115], v[96:111]
	v_exp_f32_e32 v214, v88
	v_exp_f32_e32 v215, v89
	v_exp_f32_e32 v216, v90
	v_exp_f32_e32 v217, v91
	s_waitcnt lgkmcnt(3)
	v_mfma_f32_32x32x16_bf16 v[64:79], v[128:131], v[218:221], v[64:79]
	ds_read_b128 v[80:83], v234 offset:20480
	v_exp_f32_e32 v218, v92
	v_exp_f32_e32 v219, v93
	v_exp_f32_e32 v220, v94
	v_exp_f32_e32 v221, v95
	s_waitcnt lgkmcnt(3)
	v_mfma_f32_32x32x16_bf16 v[64:79], v[132:135], v[222:225], v[64:79]
	v_add_f32_e32 v88, v180, v194
	v_add_f32_e32 v88, v181, v88
	v_add_f32_e32 v88, v182, v88
	v_add_f32_e32 v88, v183, v88
	ds_read_b128 v[84:87], v235 offset:20480
	v_add_f32_e32 v88, v193, v88
	v_add_f32_e32 v88, v189, v88
	v_add_f32_e32 v88, v190, v88
	v_add_f32_e32 v180, v192, v88
	s_waitcnt lgkmcnt(3)
	v_mfma_f32_32x32x16_bf16 v[64:79], v[136:139], v[226:229], v[64:79]
	ds_read_b128 v[88:91], v236 offset:20480
	v_exp_f32_e32 v222, v96
	v_exp_f32_e32 v223, v97
	v_exp_f32_e32 v224, v98
	v_exp_f32_e32 v225, v99
	s_waitcnt lgkmcnt(3)
	v_mfma_f32_32x32x16_bf16 v[64:79], v[140:143], v[230:233], v[64:79]
	v_add_f32_e32 v96, v173, v180
	ds_read_b128 v[92:95], v237 offset:20480
	v_add_f32_e32 v96, v174, v96
	v_add_f32_e32 v96, v175, v96
	v_add_f32_e32 v96, v176, v96
	v_add_f32_e32 v96, v191, v96
	v_add_f32_e32 v96, v188, v96
	s_waitcnt lgkmcnt(3)
	v_mfma_f32_32x32x16_bf16 v[48:63], v[128:131], v[80:83], v[48:63]
	ds_read_b128 v[80:83], v234 offset:24576
	v_exp_f32_e32 v226, v100
	v_exp_f32_e32 v227, v101
	v_exp_f32_e32 v228, v102
	v_exp_f32_e32 v229, v103
	s_waitcnt lgkmcnt(3)
	v_mfma_f32_32x32x16_bf16 v[48:63], v[132:135], v[84:87], v[48:63]
	v_add_f32_e32 v96, v171, v96
	ds_read_b128 v[84:87], v235 offset:24576
	v_add_f32_e32 v96, v172, v96
	v_add_f32_e32 v96, v185, v96
	v_add_f32_e32 v96, v186, v96
	v_add_f32_e32 v96, v187, v96
	v_add_f32_e32 v96, v184, v96
	s_waitcnt lgkmcnt(3)
	v_mfma_f32_32x32x16_bf16 v[48:63], v[136:139], v[88:91], v[48:63]
	ds_read_b128 v[88:91], v236 offset:24576
	v_exp_f32_e32 v230, v104
	v_exp_f32_e32 v231, v105
	v_exp_f32_e32 v232, v106
	v_exp_f32_e32 v233, v107
	s_waitcnt lgkmcnt(3)
	v_mfma_f32_32x32x16_bf16 v[48:63], v[140:143], v[92:95], v[48:63]
	ds_read_b128 v[92:95], v237 offset:24576
	v_add_f32_e32 v96, v177, v96
	v_add_f32_e32 v96, v178, v96
	v_add_f32_e32 v96, v179, v96
	v_add_f32_e32 v96, v161, v96
	s_waitcnt lgkmcnt(3)
	v_mfma_f32_32x32x16_bf16 v[32:47], v[128:131], v[80:83], v[32:47]
	ds_read_b128 v[80:83], v234 offset:28672
	v_exp_f32_e32 v161, v108
	v_exp_f32_e32 v234, v109
	v_exp_f32_e32 v239, v110
	v_exp_f32_e32 v240, v111
	s_waitcnt lgkmcnt(3)
	v_mfma_f32_32x32x16_bf16 v[32:47], v[132:135], v[84:87], v[32:47]
	ds_read_b128 v[84:87], v235 offset:28672
	s_waitcnt lgkmcnt(3)
	v_mfma_f32_32x32x16_bf16 v[32:47], v[136:139], v[88:91], v[32:47]
	ds_read_b128 v[88:91], v236 offset:28672
	s_waitcnt lgkmcnt(3)
	v_mfma_f32_32x32x16_bf16 v[32:47], v[140:143], v[92:95], v[32:47]
	ds_read_b128 v[92:95], v237 offset:28672
	s_waitcnt lgkmcnt(3)
	v_mfma_f32_32x32x16_bf16 v[16:31], v[128:131], v[80:83], v[16:31]
	s_add_i32 s18, s97, 0xffff8000
	s_and_b32 s18, s18, 0x18000
	s_add_i32 s19, s18, s67
	s_mov_b32 s27, m0
	s_mov_b32 m0, s19
	s_nop 0
	global_load_lds_dwordx4 v156, s[16:17]
	s_mov_b32 m0, s27
	s_waitcnt lgkmcnt(2)
	v_mfma_f32_32x32x16_bf16 v[16:31], v[132:135], v[84:87], v[16:31]
	s_addk_i32 s19, 0x400
	s_mov_b32 s27, m0
	s_mov_b32 m0, s19
	s_nop 0
	global_load_lds_dwordx4 v154, s[16:17]
	s_mov_b32 m0, s27
	s_waitcnt lgkmcnt(1)
	v_mfma_f32_32x32x16_bf16 v[16:31], v[136:139], v[88:91], v[16:31]
	s_add_i32 s18, s18, s70
	s_mov_b32 s19, m0
	s_mov_b32 m0, s18
	s_nop 0
	global_load_lds_dwordx4 v150, s[14:15]
	s_mov_b32 m0, s19
	s_waitcnt lgkmcnt(0)
	v_mfma_f32_32x32x16_bf16 v[16:31], v[140:143], v[92:95], v[16:31]
	s_addk_i32 s18, 0x400
	s_mov_b32 s19, m0
	s_mov_b32 m0, s18
	s_nop 0
	global_load_lds_dwordx4 v148, s[14:15]
	s_mov_b32 m0, s19
	s_add_i32 s18, s97, 0xffff0000
	s_and_b32 s18, s18, 0x18000
	s_add_i32 s18, s18, 0
	s_cmp_lt_u32 s61, 33
	s_cselect_b32 s34, s96, 0x8c0
	v_add_u32_e32 v132, s18, v144
	v_add_u32_e32 v133, s18, v157
	v_add_u32_e32 v136, s18, v159
	v_add_u32_e32 v137, s18, v160
	s_lshl_b64 s[18:19], s[34:35], 10
	s_add_u32 s56, s12, s18
	s_addc_u32 s57, s13, s19
	s_add_i32 s77, s26, s67
	v_add_f32_e32 v158, v158, v96
	s_waitcnt vmcnt(4) lgkmcnt(0)
	s_barrier
	s_lshl_b64 s[18:19], s[34:35], 1
	s_add_i32 s34, s77, 0x400
	ds_read_b128 v[96:99], v132
	ds_read_b128 v[100:103], v133
	ds_read_b128 v[104:107], v136
	ds_read_b128 v[108:111], v137
	s_add_u32 s18, s10, s18
	s_addc_u32 s19, s11, s19
	s_add_i32 s27, s26, s70
	s_addk_i32 s96, 0x80
	s_add_i32 s97, s97, 0x10000
	s_add_i32 s26, s27, 0x400
	s_add_u32 s14, s14, 0x100
	s_addc_u32 s15, s15, 0
	s_add_u32 s16, s16, 0x20000
	s_addc_u32 s17, s17, 0
	s_cmp_gt_u32 s61, 32
	ds_read_b128 v[172:175], v132 offset:4096
	ds_read_b128 v[176:179], v133 offset:4096
	s_waitcnt lgkmcnt(5)
	v_mfma_f32_32x32x16_bf16 v[80:95], v[96:99], v[124:127], v[0:15]
	v_cvt_pk_bf16_f32 v128, v195, v196
	v_cvt_pk_bf16_f32 v129, v197, v198
	v_cvt_pk_bf16_f32 v130, v199, v200
	v_cvt_pk_bf16_f32 v131, v201, v238
	ds_read_b128 v[180:183], v136 offset:4096
	ds_read_b128 v[184:187], v137 offset:4096
	s_waitcnt lgkmcnt(6)
	v_mfma_f32_32x32x16_bf16 v[80:95], v[100:103], v[120:123], v[80:95]
	v_cvt_pk_bf16_f32 v132, v214, v215
	v_cvt_pk_bf16_f32 v133, v216, v217
	v_cvt_pk_bf16_f32 v134, v218, v219
	v_cvt_pk_bf16_f32 v135, v220, v221
	v_add_u32_e32 v235, vcc_hi, v167
	ds_read_b128 v[188:191], v235 offset:16384
	v_add_u32_e32 v236, vcc_hi, v168
	ds_read_b128 v[202:205], v236 offset:16384
	s_waitcnt lgkmcnt(7)
	v_mfma_f32_32x32x16_bf16 v[80:95], v[104:107], v[116:119], v[80:95]
	v_cvt_pk_bf16_f32 v136, v222, v223
	v_cvt_pk_bf16_f32 v137, v224, v225
	v_cvt_pk_bf16_f32 v138, v226, v227
	v_cvt_pk_bf16_f32 v139, v228, v229
	v_add_u32_e32 v237, vcc_hi, v169
	v_add_u32_e32 v241, vcc_hi, v170
	ds_read_b128 v[206:209], v237 offset:16384
	ds_read_b128 v[210:213], v241 offset:16384
	s_waitcnt lgkmcnt(8)
	v_mfma_f32_32x32x16_bf16 v[80:95], v[108:111], v[112:115], v[80:95]
	v_cvt_pk_bf16_f32 v140, v230, v231
	v_cvt_pk_bf16_f32 v141, v232, v233
	v_cvt_pk_bf16_f32 v142, v161, v234
	v_cvt_pk_bf16_f32 v143, v239, v240
	v_add_f32_e32 v96, 0, v195
	v_add_f32_e32 v96, v196, v96
	v_add_f32_e32 v96, v197, v96
	v_add_f32_e32 v96, v198, v96
	v_add_f32_e32 v96, v199, v96
	v_add_f32_e32 v171, v200, v96
	v_add_f32_e32 v171, v201, v171
	v_add_f32_e32 v171, v238, v171
	s_waitcnt lgkmcnt(7)
	v_mfma_f32_32x32x16_bf16 v[96:111], v[172:175], v[124:127], v[0:15]
	v_exp_f32_e32 v194, v80
	v_exp_f32_e32 v195, v81
	v_exp_f32_e32 v196, v82
	v_exp_f32_e32 v197, v83
	s_waitcnt lgkmcnt(6)
	v_mfma_f32_32x32x16_bf16 v[96:111], v[176:179], v[120:123], v[96:111]
	v_exp_f32_e32 v198, v84
	v_exp_f32_e32 v200, v85
	v_exp_f32_e32 v199, v86
	v_exp_f32_e32 v201, v87
	s_waitcnt lgkmcnt(5)
	v_mfma_f32_32x32x16_bf16 v[96:111], v[180:183], v[116:119], v[96:111]
	v_exp_f32_e32 v180, v88
	v_exp_f32_e32 v181, v89
	v_exp_f32_e32 v182, v90
	v_exp_f32_e32 v183, v91
	s_waitcnt lgkmcnt(4)
	v_mfma_f32_32x32x16_bf16 v[96:111], v[184:187], v[112:115], v[96:111]
	s_waitcnt lgkmcnt(3)
	v_mfma_f32_32x32x16_bf16 v[64:79], v[128:131], v[188:191], v[64:79]
	ds_read_b128 v[80:83], v235 offset:20480
	v_exp_f32_e32 v193, v92
	v_exp_f32_e32 v189, v93
	v_exp_f32_e32 v190, v94
	v_exp_f32_e32 v192, v95
	s_waitcnt lgkmcnt(3)
	v_mfma_f32_32x32x16_bf16 v[64:79], v[132:135], v[202:205], v[64:79]
	v_add_f32_e32 v88, v214, v171
	v_add_f32_e32 v88, v215, v88
	v_add_f32_e32 v88, v216, v88
	v_add_f32_e32 v88, v217, v88
	ds_read_b128 v[84:87], v236 offset:20480
	v_add_f32_e32 v88, v218, v88
	v_add_f32_e32 v88, v219, v88
	v_add_f32_e32 v88, v220, v88
	v_add_f32_e32 v171, v221, v88
	s_waitcnt lgkmcnt(3)
	v_mfma_f32_32x32x16_bf16 v[64:79], v[136:139], v[206:209], v[64:79]
	ds_read_b128 v[88:91], v237 offset:20480
	v_exp_f32_e32 v173, v96
	v_exp_f32_e32 v174, v97
	v_exp_f32_e32 v175, v98
	v_exp_f32_e32 v176, v99
	s_waitcnt lgkmcnt(3)
	v_mfma_f32_32x32x16_bf16 v[64:79], v[140:143], v[210:213], v[64:79]
	v_add_f32_e32 v96, v222, v171
	ds_read_b128 v[92:95], v241 offset:20480
	v_add_f32_e32 v96, v223, v96
	v_add_f32_e32 v96, v224, v96
	v_add_f32_e32 v96, v225, v96
	v_add_f32_e32 v96, v226, v96
	v_add_f32_e32 v96, v227, v96
	s_waitcnt lgkmcnt(3)
	v_mfma_f32_32x32x16_bf16 v[48:63], v[128:131], v[80:83], v[48:63]
	ds_read_b128 v[80:83], v235 offset:24576
	v_exp_f32_e32 v191, v100
	v_exp_f32_e32 v188, v101
	v_exp_f32_e32 v171, v102
	v_exp_f32_e32 v172, v103
	s_waitcnt lgkmcnt(3)
	v_mfma_f32_32x32x16_bf16 v[48:63], v[132:135], v[84:87], v[48:63]
	v_add_f32_e32 v96, v228, v96
	ds_read_b128 v[84:87], v236 offset:24576
	v_add_f32_e32 v96, v229, v96
	v_add_f32_e32 v96, v230, v96
	v_add_f32_e32 v96, v231, v96
	v_add_f32_e32 v96, v232, v96
	v_add_f32_e32 v96, v233, v96
	s_waitcnt lgkmcnt(3)
	v_mfma_f32_32x32x16_bf16 v[48:63], v[136:139], v[88:91], v[48:63]
	ds_read_b128 v[88:91], v237 offset:24576
	v_exp_f32_e32 v185, v104
	v_exp_f32_e32 v186, v105
	v_exp_f32_e32 v187, v106
	v_exp_f32_e32 v184, v107
	s_waitcnt lgkmcnt(3)
	v_mfma_f32_32x32x16_bf16 v[48:63], v[140:143], v[92:95], v[48:63]
	ds_read_b128 v[92:95], v241 offset:24576
	v_add_f32_e32 v96, v161, v96
	v_add_f32_e32 v96, v234, v96
	v_add_f32_e32 v96, v239, v96
	v_add_f32_e32 v96, v240, v96
	s_waitcnt lgkmcnt(3)
	v_mfma_f32_32x32x16_bf16 v[32:47], v[128:131], v[80:83], v[32:47]
	ds_read_b128 v[80:83], v235 offset:28672
	v_exp_f32_e32 v177, v108
	v_exp_f32_e32 v178, v109
	v_exp_f32_e32 v179, v110
	v_exp_f32_e32 v161, v111
	s_waitcnt lgkmcnt(3)
	v_mfma_f32_32x32x16_bf16 v[32:47], v[132:135], v[84:87], v[32:47]
	ds_read_b128 v[84:87], v236 offset:28672
	s_waitcnt lgkmcnt(3)
	v_mfma_f32_32x32x16_bf16 v[32:47], v[136:139], v[88:91], v[32:47]
	ds_read_b128 v[88:91], v237 offset:28672
	s_waitcnt lgkmcnt(3)
	v_mfma_f32_32x32x16_bf16 v[32:47], v[140:143], v[92:95], v[32:47]
	ds_read_b128 v[92:95], v241 offset:28672
	s_waitcnt lgkmcnt(3)
	v_mfma_f32_32x32x16_bf16 v[16:31], v[128:131], v[80:83], v[16:31]
	s_mov_b32 s61, m0
	s_mov_b32 m0, s77
	s_nop 0
	global_load_lds_dwordx4 v156, s[56:57]
	s_mov_b32 m0, s61
	s_waitcnt lgkmcnt(2)
	v_mfma_f32_32x32x16_bf16 v[16:31], v[132:135], v[84:87], v[16:31]
	s_mov_b32 s61, m0
	s_mov_b32 m0, s34
	s_nop 0
	global_load_lds_dwordx4 v154, s[56:57]
	s_mov_b32 m0, s61
	s_waitcnt lgkmcnt(1)
	v_mfma_f32_32x32x16_bf16 v[16:31], v[136:139], v[88:91], v[16:31]
	s_mov_b32 s34, m0
	s_mov_b32 m0, s27
	s_nop 0
	global_load_lds_dwordx4 v150, s[18:19]
	s_mov_b32 m0, s34
	s_waitcnt lgkmcnt(0)
	v_mfma_f32_32x32x16_bf16 v[16:31], v[140:143], v[92:95], v[16:31]
	s_mov_b32 s27, m0
	s_mov_b32 m0, s26
	s_nop 0
	global_load_lds_dwordx4 v148, s[18:19]
	s_mov_b32 m0, s27
	v_add_f32_e32 v158, v158, v96
	s_mov_b32 s61, vcc_lo
	s_cbranch_scc0 .LBB0_649
	v_or_b32_e32 v80, s75, v146
	v_cmp_eq_u32_e32 vcc, 0, v80
	s_and_saveexec_b64 s[14:15], vcc
	s_cbranch_execz .LBB0_652
	v_mov_b64_e32 v[80:81], s[54:55]
	global_atomic_add v136, v[80:81], v147, off sc0
.LBB0_652:
	s_or_b64 exec, exec, s[14:15]
	s_add_i32 s14, 0, 0x18000
	v_add_u32_e32 v81, s14, v144
	v_add_u32_e32 v139, s14, v159
	v_add_u32_e32 v82, s14, v157
	v_add_u32_e32 v141, s14, v160
	s_waitcnt vmcnt(4) lgkmcnt(0)
	s_barrier
	ds_read_b128 v[96:99], v81
	ds_read_b128 v[100:103], v82
	ds_read_b128 v[104:107], v139
	ds_read_b128 v[108:111], v141
	v_or_b32_e32 v80, 0x4000, v166
	v_add_u32_e32 v142, v162, v80
	v_add_u32_e32 v140, v163, v80
	v_add_u32_e32 v138, v164, v80
	v_add_u32_e32 v137, v165, v80
	ds_read_b128 v[162:165], v81 offset:4096
	ds_read_b128 v[166:169], v82 offset:4096
	s_waitcnt lgkmcnt(5)
	v_mfma_f32_32x32x16_bf16 v[80:95], v[96:99], v[124:127], v[0:15]
	v_cvt_pk_bf16_f32 v128, v194, v195
	v_cvt_pk_bf16_f32 v129, v196, v197
	v_cvt_pk_bf16_f32 v130, v198, v200
	v_cvt_pk_bf16_f32 v131, v199, v201
	s_waitcnt lgkmcnt(4)
	v_mfma_f32_32x32x16_bf16 v[80:95], v[100:103], v[120:123], v[80:95]
	ds_read_b128 v[202:205], v139 offset:4096
	ds_read_b128 v[206:209], v141 offset:4096
	v_cvt_pk_bf16_f32 v132, v180, v181
	v_cvt_pk_bf16_f32 v133, v182, v183
	v_cvt_pk_bf16_f32 v134, v193, v189
	v_cvt_pk_bf16_f32 v135, v190, v192
	s_waitcnt lgkmcnt(5)
	v_mfma_f32_32x32x16_bf16 v[80:95], v[104:107], v[116:119], v[80:95]
	s_add_i32 s15, 0, 0x10000
	v_add_u32_e32 v139, s15, v142
	v_add_u32_e32 v141, s15, v140
	ds_read_b128 v[214:217], v139
	ds_read_b128 v[218:221], v141
	v_cvt_pk_bf16_f32 v210, v173, v174
	v_cvt_pk_bf16_f32 v211, v175, v176
	v_cvt_pk_bf16_f32 v212, v191, v188
	v_cvt_pk_bf16_f32 v213, v171, v172
	s_waitcnt lgkmcnt(6)
	v_mfma_f32_32x32x16_bf16 v[80:95], v[108:111], v[112:115], v[80:95]
	v_add_u32_e32 v143, s15, v138
	v_add_u32_e32 v144, s15, v137
	ds_read_b128 v[226:229], v143
	ds_read_b128 v[230:233], v144
	v_cvt_pk_bf16_f32 v222, v185, v186
	v_cvt_pk_bf16_f32 v223, v187, v184
	v_cvt_pk_bf16_f32 v224, v177, v178
	v_cvt_pk_bf16_f32 v225, v179, v161
	v_add_f32_e32 v96, 0, v194
	v_add_f32_e32 v96, v195, v96
	v_add_f32_e32 v96, v196, v96
	v_add_f32_e32 v96, v197, v96
	v_add_f32_e32 v96, v198, v96
	v_add_f32_e32 v157, v200, v96
	s_waitcnt lgkmcnt(7)
	v_mfma_f32_32x32x16_bf16 v[96:111], v[162:165], v[124:127], v[0:15]
	v_add_f32_e32 v124, v199, v157
	v_add_f32_e32 v124, v201, v124
	s_waitcnt lgkmcnt(6)
	v_mfma_f32_32x32x16_bf16 v[96:111], v[166:169], v[120:123], v[96:111]
	v_exp_f32_e32 v125, v80
	v_exp_f32_e32 v126, v81
	v_exp_f32_e32 v127, v82
	v_exp_f32_e32 v157, v83
	s_waitcnt lgkmcnt(5)
	v_mfma_f32_32x32x16_bf16 v[96:111], v[202:205], v[116:119], v[96:111]
	v_exp_f32_e32 v122, v84
	v_exp_f32_e32 v123, v85
	v_exp_f32_e32 v159, v86
	v_exp_f32_e32 v160, v87
	s_waitcnt lgkmcnt(4)
	v_mfma_f32_32x32x16_bf16 v[96:111], v[206:209], v[112:115], v[96:111]
	v_exp_f32_e32 v162, v88
	v_exp_f32_e32 v163, v89
	v_exp_f32_e32 v164, v90
	v_exp_f32_e32 v165, v91
	s_waitcnt lgkmcnt(3)
	v_mfma_f32_32x32x16_bf16 v[64:79], v[128:131], v[214:217], v[64:79]
	ds_read_b128 v[80:83], v139 offset:4096
	v_exp_f32_e32 v166, v92
	v_exp_f32_e32 v167, v93
	v_exp_f32_e32 v168, v94
	v_exp_f32_e32 v169, v95
	s_waitcnt lgkmcnt(3)
	v_mfma_f32_32x32x16_bf16 v[64:79], v[132:135], v[218:221], v[64:79]
	v_add_f32_e32 v88, v180, v124
	v_add_f32_e32 v88, v181, v88
	ds_read_b128 v[84:87], v141 offset:4096
	v_add_f32_e32 v88, v182, v88
	v_add_f32_e32 v88, v183, v88
	v_add_f32_e32 v88, v193, v88
	v_add_f32_e32 v88, v189, v88
	v_add_f32_e32 v88, v190, v88
	v_add_f32_e32 v112, v192, v88
	s_waitcnt lgkmcnt(3)
	v_mfma_f32_32x32x16_bf16 v[64:79], v[210:213], v[226:229], v[64:79]
	ds_read_b128 v[88:91], v143 offset:4096
	v_exp_f32_e32 v124, v96
	v_exp_f32_e32 v170, v97
	v_exp_f32_e32 v180, v98
	v_exp_f32_e32 v181, v99
	s_waitcnt lgkmcnt(3)
	v_mfma_f32_32x32x16_bf16 v[64:79], v[222:225], v[230:233], v[64:79]
	ds_read_b128 v[92:95], v144 offset:4096
	v_add_f32_e32 v96, v173, v112
	v_add_f32_e32 v96, v174, v96
	v_add_f32_e32 v96, v175, v96
	v_add_f32_e32 v96, v176, v96
	v_add_f32_e32 v96, v191, v96
	v_add_f32_e32 v112, v188, v96
	s_waitcnt lgkmcnt(3)
	v_mfma_f32_32x32x16_bf16 v[48:63], v[128:131], v[80:83], v[48:63]
	ds_read_b128 v[96:99], v139 offset:8192
	v_exp_f32_e32 v173, v100
	v_exp_f32_e32 v174, v101
	v_exp_f32_e32 v175, v102
	v_exp_f32_e32 v176, v103
	s_waitcnt lgkmcnt(3)
	v_mfma_f32_32x32x16_bf16 v[48:63], v[132:135], v[84:87], v[48:63]
	ds_read_b128 v[80:83], v141 offset:8192
	v_add_f32_e32 v100, v171, v112
	v_add_f32_e32 v100, v172, v100
	v_add_f32_e32 v100, v185, v100
	v_add_f32_e32 v100, v186, v100
	v_add_f32_e32 v100, v187, v100
	v_add_f32_e32 v100, v184, v100
	s_waitcnt lgkmcnt(3)
	v_mfma_f32_32x32x16_bf16 v[48:63], v[210:213], v[88:91], v[48:63]
	ds_read_b128 v[84:87], v143 offset:8192
	v_exp_f32_e32 v171, v104
	v_exp_f32_e32 v172, v105
	v_exp_f32_e32 v182, v106
	v_exp_f32_e32 v183, v107
	s_waitcnt lgkmcnt(3)
	v_mfma_f32_32x32x16_bf16 v[48:63], v[222:225], v[92:95], v[48:63]
	ds_read_b128 v[88:91], v144 offset:8192
	v_add_f32_e32 v100, v177, v100
	v_add_f32_e32 v100, v178, v100
	v_add_f32_e32 v177, v179, v100
	s_waitcnt lgkmcnt(3)
	v_mfma_f32_32x32x16_bf16 v[32:47], v[128:131], v[96:99], v[32:47]
	ds_read_b128 v[92:95], v139 offset:12288
	v_exp_f32_e32 v178, v108
	v_exp_f32_e32 v179, v109
	v_exp_f32_e32 v184, v110
	v_exp_f32_e32 v185, v111
	s_waitcnt lgkmcnt(3)
	v_mfma_f32_32x32x16_bf16 v[32:47], v[132:135], v[80:83], v[32:47]
	ds_read_b128 v[96:99], v141 offset:12288
	s_waitcnt lgkmcnt(3)
	v_mfma_f32_32x32x16_bf16 v[32:47], v[210:213], v[84:87], v[32:47]
	ds_read_b128 v[80:83], v143 offset:12288
	s_waitcnt lgkmcnt(3)
	v_mfma_f32_32x32x16_bf16 v[32:47], v[222:225], v[88:91], v[32:47]
	ds_read_b128 v[84:87], v144 offset:12288
	s_waitcnt lgkmcnt(3)
	v_mfma_f32_32x32x16_bf16 v[16:31], v[128:131], v[92:95], v[16:31]
	s_add_u32 s12, s12, 0x230000
	s_addc_u32 s13, s13, 0
	s_mov_b32 s15, m0
	s_mov_b32 m0, s71
	s_nop 0
	global_load_lds_dwordx4 v156, s[12:13]
	s_mov_b32 m0, s15
	s_waitcnt lgkmcnt(2)
	v_mfma_f32_32x32x16_bf16 v[16:31], v[132:135], v[96:99], v[16:31]
	s_mov_b32 s15, m0
	s_mov_b32 m0, s72
	s_nop 0
	global_load_lds_dwordx4 v154, s[12:13]
	s_mov_b32 m0, s15
	s_waitcnt lgkmcnt(1)
	v_mfma_f32_32x32x16_bf16 v[16:31], v[210:213], v[80:83], v[16:31]
	s_add_u32 s10, s10, 0x1180
	s_addc_u32 s11, s11, 0
	s_mov_b32 s12, m0
	s_mov_b32 m0, s73
	s_nop 0
	global_load_lds_dwordx4 v150, s[10:11]
	s_mov_b32 m0, s12
	s_waitcnt lgkmcnt(0)
	v_mfma_f32_32x32x16_bf16 v[16:31], v[222:225], v[84:87], v[16:31]
	s_mov_b32 s12, m0
	s_mov_b32 m0, s78
	s_nop 0
	global_load_lds_dwordx4 v148, s[10:11]
	s_mov_b32 m0, s12
	v_add_u32_e32 v80, s14, v142
	v_cvt_pk_bf16_f32 v98, v125, v126
	v_cvt_pk_bf16_f32 v99, v127, v157
	v_cvt_pk_bf16_f32 v100, v122, v123
	v_cvt_pk_bf16_f32 v101, v159, v160
	ds_read_b128 v[80:83], v80
	v_add_u32_e32 v84, s14, v140
	ds_read_b128 v[84:87], v84
	s_waitcnt lgkmcnt(1)
	v_mfma_f32_32x32x16_bf16 v[64:79], v[98:101], v[80:83], v[64:79]
	v_cvt_pk_bf16_f32 v102, v162, v163
	v_cvt_pk_bf16_f32 v103, v164, v165
	v_cvt_pk_bf16_f32 v104, v166, v167
	v_cvt_pk_bf16_f32 v105, v168, v169
	v_add_u32_e32 v80, s14, v138
	v_cvt_pk_bf16_f32 v106, v124, v170
	v_cvt_pk_bf16_f32 v107, v180, v181
	s_waitcnt lgkmcnt(0)
	v_mfma_f32_32x32x16_bf16 v[64:79], v[102:105], v[84:87], v[64:79]
	v_cvt_pk_bf16_f32 v108, v173, v174
	v_cvt_pk_bf16_f32 v109, v175, v176
	ds_read_b128 v[80:83], v80
	v_add_u32_e32 v84, s14, v137
	ds_read_b128 v[84:87], v84
	v_cvt_pk_bf16_f32 v110, v171, v172
	v_cvt_pk_bf16_f32 v111, v182, v183
	s_waitcnt lgkmcnt(1)
	v_mfma_f32_32x32x16_bf16 v[64:79], v[106:109], v[80:83], v[64:79]
	v_cvt_pk_bf16_f32 v112, v178, v179
	v_cvt_pk_bf16_f32 v113, v184, v185
	v_add_u32_e32 v80, s91, v142
	ds_read_b128 v[80:83], v80
	v_ashrrev_i32_e32 v88, 4, v146
	v_add_u32_e32 v139, s69, v88
	s_lshl_b32 s10, s60, 1
	s_waitcnt lgkmcnt(1)
	v_mfma_f32_32x32x16_bf16 v[64:79], v[110:113], v[84:87], v[64:79]
	v_add_u32_e32 v84, s91, v140
	ds_read_b128 v[84:87], v84
	v_add_u32_e32 v96, s59, v139
	s_add_u32 s4, s4, s10
	s_addc_u32 s5, s5, 0
	v_ashrrev_i32_e32 v97, 31, v96
	v_add_u32_e32 v118, s92, v140
	s_waitcnt lgkmcnt(1)
	v_mfma_f32_32x32x16_bf16 v[48:63], v[98:101], v[80:83], v[48:63]
	v_lshlrev_b32_e32 v80, 3, v146
	v_and_b32_e32 v143, 0x78, v80
	v_add_u32_e32 v80, s91, v138
	ds_read_b128 v[80:83], v80
	v_lshlrev_b32_e32 v144, 1, v143
	v_lshl_add_u64 v[88:89], s[4:5], 0, v[144:145]
	s_mov_b32 s4, 0x9c01000
	s_waitcnt lgkmcnt(1)
	v_mfma_f32_32x32x16_bf16 v[48:63], v[102:105], v[84:87], v[48:63]
	v_lshlrev_b64 v[84:85], 10, v[96:97]
	v_lshl_add_u64 v[114:115], v[88:89], 0, v[84:85]
	v_add_u32_e32 v84, s91, v137
	ds_read_b128 v[84:87], v84
	v_add_f32_e32 v125, 0, v125
	s_waitcnt lgkmcnt(1)
	v_mfma_f32_32x32x16_bf16 v[48:63], v[106:109], v[80:83], v[48:63]
	v_add_co_u32_e64 v80, s[4:5], s4, v114
	s_nop 1
	v_addc_co_u32_e64 v81, s[4:5], 0, v115, s[4:5]
	s_mov_b32 s4, 0x9c03000
	global_load_dwordx4 v[92:95], v[80:81], off offset:-4096
	global_load_dwordx4 v[88:91], v[80:81], off
	v_add_co_u32_e64 v80, s[4:5], s4, v114
	s_waitcnt lgkmcnt(0)
	v_mfma_f32_32x32x16_bf16 v[48:63], v[110:113], v[84:87], v[48:63]
	v_addc_co_u32_e64 v81, s[4:5], 0, v115, s[4:5]
	global_load_dwordx4 v[84:87], v[80:81], off offset:-4096
	s_nop 0
	global_load_dwordx4 v[80:83], v[80:81], off
	v_add_u32_e32 v114, s92, v142
	ds_read_b128 v[114:117], v114
	ds_read_b128 v[118:121], v118
	s_waitcnt lgkmcnt(1)
	v_mfma_f32_32x32x16_bf16 v[32:47], v[98:101], v[114:117], v[32:47]
	v_add_f32_e32 v114, 0, v124
	v_add_f32_e32 v115, v126, v125
	v_add_f32_e32 v114, v170, v114
	v_add_f32_e32 v115, v127, v115
	v_add_f32_e32 v114, v180, v114
	v_add_f32_e32 v115, v157, v115
	v_add_f32_e32 v124, v181, v114
	s_waitcnt lgkmcnt(0)
	v_mfma_f32_32x32x16_bf16 v[32:47], v[102:105], v[118:121], v[32:47]
	v_add_u32_e32 v114, s92, v138
	v_add_f32_e32 v118, v122, v115
	ds_read_b128 v[114:117], v114
	v_add_f32_e32 v123, v123, v118
	v_add_u32_e32 v118, s92, v137
	ds_read_b128 v[118:121], v118
	v_add_f32_e32 v122, v173, v124
	s_waitcnt lgkmcnt(1)
	v_mfma_f32_32x32x16_bf16 v[32:47], v[106:109], v[114:117], v[32:47]
	v_add_f32_e32 v114, v174, v122
	v_add_f32_e32 v115, v159, v123
	v_add_f32_e32 v114, v175, v114
	v_add_f32_e32 v115, v160, v115
	v_add_f32_e32 v114, v176, v114
	v_add_f32_e32 v115, v162, v115
	v_add_f32_e32 v122, v171, v114
	v_add_u32_e32 v114, s93, v142
	s_waitcnt lgkmcnt(0)
	v_mfma_f32_32x32x16_bf16 v[32:47], v[110:113], v[118:121], v[32:47]
	v_add_f32_e32 v118, v163, v115
	ds_read_b128 v[114:117], v114
	v_add_f32_e32 v123, v164, v118
	v_add_u32_e32 v118, s93, v140
	ds_read_b128 v[118:121], v118
	v_add_f32_e32 v122, v172, v122
	s_waitcnt lgkmcnt(1)
	v_mfma_f32_32x32x16_bf16 v[16:31], v[98:101], v[114:117], v[16:31]
	v_add_f32_e32 v98, v182, v122
	v_add_f32_e32 v99, v165, v123
	v_add_f32_e32 v98, v183, v98
	v_add_f32_e32 v99, v166, v99
	v_add_f32_e32 v98, v178, v98
	v_add_f32_e32 v99, v167, v99
	v_add_f32_e32 v114, v179, v98
	s_waitcnt lgkmcnt(0)
	v_mfma_f32_32x32x16_bf16 v[16:31], v[102:105], v[118:121], v[16:31]
	v_add_u32_e32 v98, s93, v138
	v_add_f32_e32 v102, v168, v99
	ds_read_b128 v[98:101], v98
	v_add_f32_e32 v115, v169, v102
	v_add_u32_e32 v102, s93, v137
	ds_read_b128 v[102:105], v102
	v_add_f32_e32 v114, v184, v114
	s_waitcnt lgkmcnt(1)
	v_mfma_f32_32x32x16_bf16 v[16:31], v[106:109], v[98:101], v[16:31]
	v_add_f32_e32 v98, v185, v114
	v_add_f32_e32 v99, v161, v177
	v_add_f32_e32 v98, v115, v98
	v_add_f32_e32 v99, v158, v99
	v_lshlrev_b32_e32 v115, 2, v146
	v_add_f32_e32 v98, v99, v98
	v_xor_b32_e32 v99, 0x80, v115
	s_waitcnt lgkmcnt(0)
	v_mfma_f32_32x32x16_bf16 v[16:31], v[110:113], v[102:105], v[16:31]
	ds_bpermute_b32 v99, v99, v98
	s_waitcnt vmcnt(0) lgkmcnt(0)
	s_barrier
	s_and_saveexec_b64 s[4:5], vcc
	s_cbranch_execz .LBB0_654
	v_mov_b32_e32 v100, s89
	ds_write_b32 v100, v136
